# phase-0 rownorm: early vmcnt(1) removed, 12 of the 16 row loads issued before the first wait
# speedup vs baseline: 1.0042x; 1.0042x over previous
.LBB0_49:
	v_lshrrev_b32_e32 v1, 3, v2
	v_and_b32_e32 v0, 0x700, v80
	v_and_b32_e32 v1, 0xf8, v1
	v_and_b32_e32 v3, 0xfffff807, v2
	v_or3_b32 v0, v0, v3, v1
	v_cndmask_b32_e32 v0, v2, v0, vcc
	v_ashrrev_i32_e32 v1, 31, v0
	v_lshlrev_b64 v[4:5], 12, v[0:1]
	v_lshl_add_u64 v[4:5], v[66:67], 0, v[4:5]
	s_waitcnt lgkmcnt(0)
	global_load_dwordx4 v[48:51], v[4:5], off
	global_load_dwordx4 v[52:55], v[4:5], off offset:1024
	global_load_dwordx4 v[56:59], v[4:5], off offset:2048
	global_load_dwordx4 v[60:63], v[4:5], off offset:3072
	v_add_u32_e32 v3, s18, v2
	v_cmp_gt_i32_e64 s[6:7], s3, v3
	v_lshlrev_b64 v[0:1], 11, v[0:1]
	v_cndmask_b32_e64 v4, v2, v3, s[6:7]
	v_lshlrev_b32_e32 v5, 5, v4
	v_lshrrev_b32_e32 v6, 3, v4
	v_and_b32_e32 v7, 0xfffff807, v4
	v_and_b32_e32 v5, 0x700, v5
	v_and_b32_e32 v6, 0xf8, v6
	v_or3_b32 v5, v5, v7, v6
	v_cndmask_b32_e32 v72, v4, v5, vcc
	v_ashrrev_i32_e32 v73, 31, v72
	v_lshlrev_b64 v[4:5], 12, v[72:73]
	v_lshl_add_u64 v[4:5], v[66:67], 0, v[4:5]
	global_load_dwordx4 v[16:19], v[4:5], off offset:1024
	global_load_dwordx4 v[32:35], v[4:5], off
	global_load_dwordx4 v[20:23], v[4:5], off offset:2048
	v_add_u32_e32 v3, s18, v3
	v_cmp_gt_i32_e64 s[8:9], s3, v3
	global_load_dwordx4 v[12:15], v[4:5], off offset:3072
	v_add_u32_e32 v82, s18, v3
	v_cndmask_b32_e64 v4, v2, v3, s[8:9]
	v_lshlrev_b32_e32 v3, 5, v4
	v_lshrrev_b32_e32 v5, 3, v4
	v_cmp_gt_i32_e64 s[4:5], s3, v82
	v_and_b32_e32 v6, 0xfffff807, v4
	v_and_b32_e32 v3, 0x700, v3
	v_cndmask_b32_e64 v2, v2, v82, s[4:5]
	v_and_b32_e32 v5, 0xf8, v5
	v_lshlrev_b32_e32 v7, 5, v2
	v_lshrrev_b32_e32 v8, 3, v2
	v_or3_b32 v3, v3, v6, v5
	v_and_b32_e32 v9, 0xfffff807, v2
	v_and_b32_e32 v5, 0x700, v7
	v_and_b32_e32 v6, 0xf8, v8
	v_cndmask_b32_e32 v70, v4, v3, vcc
	v_or3_b32 v3, v5, v9, v6
	v_ashrrev_i32_e32 v71, 31, v70
	v_cndmask_b32_e32 v68, v2, v3, vcc
	v_lshlrev_b64 v[2:3], 12, v[70:71]
	v_lshl_add_u64 v[2:3], v[66:67], 0, v[2:3]
	global_load_dwordx4 v[44:47], v[2:3], off
	global_load_dwordx4 v[36:39], v[2:3], off offset:1024
	global_load_dwordx4 v[40:43], v[2:3], off offset:2048
	global_load_dwordx4 v[28:31], v[2:3], off offset:3072
	s_waitcnt vmcnt(8)
	v_mov_b32_e32 v84, v57
	v_mov_b32_e32 v8, v49
	v_mov_b32_e32 v9, v53
	v_mov_b32_e32 v6, v48
	v_mov_b32_e32 v7, v52
	v_mov_b32_e32 v85, v61
	v_pk_mul_f32 v[8:9], v[8:9], v[8:9]
	v_mov_b32_e32 v2, v50
	v_mov_b32_e32 v3, v54
	v_mov_b32_e32 v26, v56
	v_mov_b32_e32 v27, v60
	v_pk_mul_f32 v[84:85], v[84:85], v[84:85]
	v_pk_fma_f32 v[6:7], v[6:7], v[6:7], v[8:9]
	v_mov_b32_e32 v4, v51
	v_mov_b32_e32 v5, v55
	v_mov_b32_e32 v10, v58
	v_mov_b32_e32 v11, v62
	v_pk_fma_f32 v[8:9], v[26:27], v[26:27], v[84:85]
	v_pk_fma_f32 v[2:3], v[2:3], v[2:3], v[6:7]
	v_mov_b32_e32 v24, v59
	v_mov_b32_e32 v25, v63
	v_pk_fma_f32 v[6:7], v[10:11], v[10:11], v[8:9]
	v_pk_fma_f32 v[2:3], v[4:5], v[4:5], v[2:3]
	v_pk_fma_f32 v[4:5], v[24:25], v[24:25], v[6:7]
	v_add_f32_e32 v2, v2, v3
	v_add_f32_e32 v2, v2, v4
	v_add_f32_e32 v8, v2, v5
	ds_bpermute_b32 v9, v74, v8
	v_ashrrev_i32_e32 v69, 31, v68
	v_lshlrev_b64 v[2:3], 12, v[68:69]
	v_lshl_add_u64 v[2:3], v[66:67], 0, v[2:3]
	global_load_dwordx4 v[4:7], v[2:3], off offset:1024
	global_load_dwordx4 v[24:27], v[2:3], off
	s_waitcnt lgkmcnt(0)
	v_add_f32_e32 v8, v8, v9
	ds_bpermute_b32 v9, v75, v8
	v_lshl_add_u64 v[84:85], v[64:65], 0, v[0:1]
	s_waitcnt lgkmcnt(0)
	v_add_f32_e32 v83, v8, v9
	global_load_dwordx4 v[8:11], v[2:3], off offset:2048
	s_nop 0
	global_load_dwordx4 v[0:3], v[2:3], off offset:3072
	ds_bpermute_b32 v88, v76, v83
	s_waitcnt lgkmcnt(0)
	v_add_f32_e32 v83, v83, v88
	ds_bpermute_b32 v96, v77, v83
	s_waitcnt lgkmcnt(0)
	v_add_f32_e32 v83, v83, v96
	ds_bpermute_b32 v100, v78, v83
	s_waitcnt vmcnt(11)
	v_pk_mul_f32 v[86:87], v[16:17], v[16:17]
	s_waitcnt vmcnt(10)
	v_pk_mul_f32 v[90:91], v[32:33], v[32:33]
	v_add_f32_e32 v86, v86, v87
	v_add_f32_e32 v87, v90, v91
	s_waitcnt lgkmcnt(0)
	v_add_f32_e32 v83, v83, v100
	ds_bpermute_b32 v90, v79, v83
	v_pk_mul_f32 v[88:89], v[18:19], v[18:19]
	v_pk_mul_f32 v[92:93], v[34:35], v[34:35]
	v_add_f32_e32 v86, v86, v88
	s_waitcnt vmcnt(9)
	v_pk_mul_f32 v[94:95], v[20:21], v[20:21]
	s_waitcnt lgkmcnt(0)
	v_add_f32_e32 v83, v83, v90
	v_fmamk_f32 v83, v83, 0x3a800000, v81
	v_mul_f32_e32 v90, 0x4b800000, v83
	v_cmp_gt_f32_e64 s[10:11], s22, v83
	v_add_f32_e32 v87, v87, v92
	v_pk_mul_f32 v[96:97], v[22:23], v[22:23]
	v_cndmask_b32_e64 v83, v83, v90, s[10:11]
	v_rsq_f32_e32 v83, v83
	v_add_f32_e32 v90, v86, v89
	s_waitcnt vmcnt(8)
	v_pk_mul_f32 v[98:99], v[12:13], v[12:13]
	v_add_f32_e32 v91, v94, v95
	v_mul_f32_e32 v86, 0x45800000, v83
	v_cndmask_b32_e64 v86, v83, v86, s[10:11]
	v_pk_mul_f32 v[48:49], v[48:49], v[86:87] op_sel_hi:[1,0]
	v_pk_mul_f32 v[50:51], v[50:51], v[86:87] op_sel_hi:[1,0]
	v_add_f32_e32 v88, v91, v96
	v_add_f32_e32 v91, v87, v93
	v_pk_mul_f32 v[52:53], v[52:53], v[86:87] op_sel_hi:[1,0]
	v_pk_mul_f32 v[54:55], v[54:55], v[86:87] op_sel_hi:[1,0]
	v_pk_mul_f32 v[56:57], v[56:57], v[86:87] op_sel_hi:[1,0]
	v_pk_mul_f32 v[58:59], v[58:59], v[86:87] op_sel_hi:[1,0]
	v_pk_mul_f32 v[60:61], v[60:61], v[86:87] op_sel_hi:[1,0]
	v_pk_mul_f32 v[62:63], v[62:63], v[86:87] op_sel_hi:[1,0]
	v_cvt_pk_bf16_f32 v86, v48, v49
	v_cvt_pk_bf16_f32 v87, v50, v51
	v_add_f32_e32 v50, v98, v99
	v_pk_mul_f32 v[48:49], v[14:15], v[14:15]
	v_add_f32_e32 v92, v88, v97
	v_add_f32_e32 v48, v50, v48
	v_add_f32_e32 v50, v48, v49
	s_waitcnt vmcnt(6)
	v_pk_mul_f32 v[48:49], v[36:37], v[36:37]
	v_cvt_pk_bf16_f32 v88, v52, v53
	v_add_f32_e32 v51, v48, v49
	v_pk_mul_f32 v[48:49], v[38:39], v[38:39]
	v_cvt_pk_bf16_f32 v89, v54, v55
	v_add_f32_e32 v48, v51, v48
	v_add_f32_e32 v51, v48, v49
	v_pk_mul_f32 v[48:49], v[44:45], v[44:45]
	v_cvt_pk_bf16_f32 v54, v56, v57
	v_add_f32_e32 v52, v48, v49
	v_pk_mul_f32 v[48:49], v[46:47], v[46:47]
	v_cvt_pk_bf16_f32 v55, v58, v59
	v_add_f32_e32 v48, v52, v48
	v_add_f32_e32 v52, v48, v49
	s_waitcnt vmcnt(5)
	v_pk_mul_f32 v[48:49], v[40:41], v[40:41]
	s_nop 0
	v_add_f32_e32 v53, v48, v49
	v_pk_mul_f32 v[48:49], v[42:43], v[42:43]
	s_nop 0
	v_add_f32_e32 v48, v53, v48
	v_add_f32_e32 v53, v48, v49
	s_waitcnt vmcnt(4)
	v_pk_mul_f32 v[48:49], v[28:29], v[28:29]
	s_nop 0
	v_add_f32_e32 v56, v48, v49
	v_pk_mul_f32 v[48:49], v[30:31], v[30:31]
	s_nop 0
	v_add_f32_e32 v48, v56, v48
	v_add_f32_e32 v56, v48, v49
	s_waitcnt vmcnt(3)
	v_pk_mul_f32 v[48:49], v[4:5], v[4:5]
	s_nop 0
	v_add_f32_e32 v57, v48, v49
	v_pk_mul_f32 v[48:49], v[6:7], v[6:7]
	s_nop 0
	v_add_f32_e32 v48, v57, v48
	v_add_f32_e32 v57, v48, v49
	s_waitcnt vmcnt(2)
	v_pk_mul_f32 v[48:49], v[24:25], v[24:25]
	s_nop 0
	v_add_f32_e32 v58, v48, v49
	v_pk_mul_f32 v[48:49], v[26:27], v[26:27]
	s_nop 0
	v_add_f32_e32 v48, v58, v48
	v_add_f32_e32 v58, v48, v49
	s_waitcnt vmcnt(1)
	v_pk_mul_f32 v[48:49], v[8:9], v[8:9]
	s_nop 0
	v_add_f32_e32 v59, v48, v49
	v_pk_mul_f32 v[48:49], v[10:11], v[10:11]
	s_nop 0
	v_add_f32_e32 v48, v59, v48
	v_add_f32_e32 v59, v48, v49
	s_waitcnt vmcnt(0)
	v_pk_mul_f32 v[48:49], v[0:1], v[0:1]
	s_nop 0
	v_add_f32_e32 v83, v48, v49
	v_pk_mul_f32 v[48:49], v[2:3], v[2:3]
	s_nop 0
	v_add_f32_e32 v48, v83, v48
	v_add_f32_e32 v48, v48, v49
	v_add_f32_e32 v49, v91, v90
	v_add_f32_e32 v49, v49, v92
	v_add_f32_e32 v49, v49, v50
	v_add_f32_e32 v50, v52, v51
	v_add_f32_e32 v51, v58, v57
	v_add_f32_e32 v50, v50, v53
	v_add_f32_e32 v51, v51, v59
	v_add_f32_e32 v50, v50, v56
	v_add_f32_e32 v48, v51, v48
	ds_bpermute_b32 v52, v74, v49
	ds_bpermute_b32 v53, v74, v50
	ds_bpermute_b32 v51, v74, v48
	v_cvt_pk_bf16_f32 v56, v60, v61
	v_cvt_pk_bf16_f32 v57, v62, v63
	s_waitcnt lgkmcnt(2)
	v_add_f32_e32 v49, v49, v52
	s_waitcnt lgkmcnt(1)
	v_add_f32_e32 v50, v50, v53
	s_waitcnt lgkmcnt(0)
	v_add_f32_e32 v48, v48, v51
	ds_bpermute_b32 v52, v75, v49
	ds_bpermute_b32 v53, v75, v50
	ds_bpermute_b32 v51, v75, v48
	global_store_dwordx2 v[84:85], v[86:87], off
	global_store_dwordx2 v[84:85], v[88:89], off offset:512
	global_store_dwordx2 v[84:85], v[54:55], off offset:1024
	global_store_dwordx2 v[84:85], v[56:57], off offset:1536
	s_waitcnt lgkmcnt(2)
	v_add_f32_e32 v49, v49, v52
	s_waitcnt lgkmcnt(1)
	v_add_f32_e32 v50, v50, v53
	s_waitcnt lgkmcnt(0)
	v_add_f32_e32 v48, v48, v51
	ds_bpermute_b32 v52, v76, v49
	ds_bpermute_b32 v53, v76, v50
	ds_bpermute_b32 v51, v76, v48
	s_waitcnt lgkmcnt(2)
	v_add_f32_e32 v49, v49, v52
	s_waitcnt lgkmcnt(1)
	v_add_f32_e32 v50, v50, v53
	s_waitcnt lgkmcnt(0)
	v_add_f32_e32 v48, v48, v51
	ds_bpermute_b32 v52, v77, v49
	ds_bpermute_b32 v53, v77, v50
	ds_bpermute_b32 v51, v77, v48
	s_waitcnt lgkmcnt(2)
	v_add_f32_e32 v49, v49, v52
	s_waitcnt lgkmcnt(1)
	v_add_f32_e32 v50, v50, v53
	s_waitcnt lgkmcnt(0)
	v_add_f32_e32 v48, v48, v51
	ds_bpermute_b32 v52, v78, v49
	ds_bpermute_b32 v53, v78, v50
	ds_bpermute_b32 v51, v78, v48
	s_waitcnt lgkmcnt(2)
	v_add_f32_e32 v52, v49, v52
	s_waitcnt lgkmcnt(1)
	v_add_f32_e32 v50, v50, v53
	s_waitcnt lgkmcnt(0)
	v_add_f32_e32 v48, v48, v51
	ds_bpermute_b32 v53, v79, v52
	ds_bpermute_b32 v51, v79, v50
	ds_bpermute_b32 v49, v79, v48
	s_and_saveexec_b64 s[10:11], s[6:7]
	s_cbranch_execnz .LBB0_52
	s_or_b64 exec, exec, s[10:11]
	s_and_saveexec_b64 s[10:11], s[8:9]
	s_cbranch_execnz .LBB0_53
